# seam after PREP uses the XCD-aware barrier (copy of the other seams) instead of cooperative_groups grid sync
# speedup vs baseline: 1.0099x; 1.0023x over previous
.LBB0_59:
	s_or_b64 exec, exec, s[4:5]
	s_cmp_gt_i32 s93, 1
	s_cselect_b64 s[0:1], -1, 0
	s_cmp_lg_u32 s94, 0
	s_cselect_b64 s[4:5], -1, 0
	s_and_b64 s[0:1], s[0:1], s[4:5]
	s_andn2_b64 vcc, exec, s[0:1]
	s_cbranch_vccnz .LBB0_71
	s_load_dword s0, s[96:97], 0xd0
	s_add_u32 s8, s96, 0xd0
	s_addc_u32 s9, s97, 0
	s_waitcnt lgkmcnt(0)
	s_waitcnt vmcnt(0)
	s_waitcnt vmcnt(0) lgkmcnt(0)
	s_barrier
	s_and_saveexec_b64 s[4:5], s[90:91]
	s_cbranch_execz .Lxb0_193
	s_add_i32 s1, 0, 0x20080
	v_mov_b32_e32 v0, s1
	s_waitcnt vmcnt(0) expcnt(0) lgkmcnt(0)
	ds_read_b32 v2, v0
	s_add_i32 s1, 0, 0x20084
	v_mov_b32_e32 v0, s1
	ds_read_b32 v0, v0
	s_waitcnt lgkmcnt(1)
	v_cmp_ne_u32_e32 vcc, 0, v2
	s_cbranch_vccnz .Lxb0_161
	s_load_dwordx2 s[10:11], s[8:9], 0x4
	s_add_u32 s6, s86, 0x1000
	s_addc_u32 s7, s87, 0
	s_add_u32 s8, s86, 0x1100
	s_addc_u32 s9, s87, 0
	s_waitcnt lgkmcnt(0)
	s_mul_i32 s0, s10, s0
	s_add_u32 s10, s86, 0x1200
	s_mul_i32 s0, s0, s11
	s_addc_u32 s11, s87, 0
	s_add_u32 s12, s86, 0x1300
	s_addc_u32 s13, s87, 0
	s_mov_b32 s1, 1
	v_mov_b32_e32 v16, 0
	s_branch .Lxb0_149

.Lxb0_193:
	s_or_b64 exec, exec, s[4:5]
	s_waitcnt lgkmcnt(0)
	s_barrier
.LBB0_71:
	s_cmp_lt_i32 s92, 2
	s_cselect_b64 s[0:1], -1, 0
	s_cmp_gt_i32 s93, 1
	s_cselect_b64 s[4:5], -1, 0
	s_and_b64 s[0:1], s[0:1], s[4:5]
	s_andn2_b64 vcc, exec, s[0:1]
	s_cbranch_vccnz .LBB0_194
	v_lshrrev_b32_e32 v2, 5, v160
	v_lshrrev_b32_e32 v4, 1, v160
	v_and_b32_e32 v2, 4, v2
	v_bfe_u32 v3, v160, 2, 2
	v_and_b32_e32 v147, 24, v4
	v_lshlrev_b32_e32 v0, 4, v160
	v_and_b32_e32 v1, 32, v160
	v_bfe_u32 v146, v160, 2, 4
	v_or3_b32 v2, v2, v3, v147
	v_lshrrev_b32_e32 v3, 3, v160
	s_movk_i32 s4, 0x70
	v_bitop3_b32 v144, v0, v1, 48 bitop3:0x6c
	v_and_b32_e32 v145, 64, v160
	v_and_or_b32 v4, v3, s4, v146
	s_movk_i32 s4, 0x60
	v_add_u32_e32 v148, 0x2000, v0
	s_add_u32 s8, s96, 0xd0
	v_or_b32_e32 v1, v144, v145
	v_and_or_b32 v3, v3, s4, v2
	v_lshrrev_b32_e32 v0, 7, v148
	s_movk_i32 s4, 0xf0
	s_addc_u32 s9, s97, 0
	s_load_dword s0, s[96:97], 0xd0
	v_lshl_or_b32 v130, v3, 11, v1
	v_and_or_b32 v3, v0, s4, v146
	s_movk_i32 s4, 0xe0
	s_add_u32 s1, s86, 0x4000000
	v_and_or_b32 v0, v0, s4, v2
	s_addc_u32 s3, s87, 0
	v_lshl_or_b32 v128, v4, 11, v1
	v_lshl_or_b32 v132, v3, 11, v1
	v_lshl_or_b32 v134, v0, 11, v1
	v_lshlrev_b32_e32 v0, 6, v160
	v_lshlrev_b32_e32 v1, 2, v160
	v_lshlrev_b32_e32 v150, 1, v147
	v_and_b32_e32 v0, 0x3c0, v0
	v_and_b32_e32 v1, 32, v1
	s_cmpk_lt_i32 s2, 0x400
	v_readfirstlane_b32 s33, v160
	v_and_b32_e32 v149, 15, v160
	s_cselect_b64 s[10:11], -1, 0
	s_cmpk_gt_i32 s2, 0x3ff
	v_bitop3_b32 v151, v150, v1, v0 bitop3:0x36
	s_cbranch_scc1 .LBB0_104
	s_ashr_i32 s38, s2, 31
	s_lshr_b32 s4, s38, 29
	s_add_i32 s6, s2, s4
	s_and_b32 s4, s6, -8
	s_sub_i32 s12, s2, s4
	s_cmp_gt_i32 s12, -1
	s_cbranch_scc0 .LBB0_75
	s_lshl_b32 s7, s12, 7
	s_cbranch_execz .LBB0_76
	s_branch .LBB0_77
